# attn main loop re-emitted: -mhat in QK C operand, Q in regs, K reloads in phase A, max tree inside PV gaps
# speedup vs baseline: 1.0256x; 1.0256x over previous
.LBB5_820:
	v_lshlrev_b32_e32 v32, 1, v202
	v_and_b32_e32 v185, 32, v32
	v_lshlrev_b32_e32 v33, 8, v204
	s_movk_i32 s0, 0xc0
	v_add_u32_e32 v32, 0, v185
	v_and_or_b32 v187, v206, s0, v33
	v_add3_u32 v212, v32, v205, v187
	v_max3_f32 v32, v16, v17, v0
	v_max3_f32 v33, v18, v19, v1
	s_waitcnt vmcnt(0) lgkmcnt(0)
	s_barrier
	s_cmp_lg_u32 0, -1
	v_max3_f32 v32, v32, v2, v3
	v_max3_f32 v33, v33, v22, v23
	s_mov_b32 s48, 1
	v_max3_f32 v32, v32, v20, v21
	v_max3_f32 v33, v33, v6, v7
	s_mov_b32 s3, 0
	v_max3_f32 v32, v32, v4, v5
	v_max3_f32 v33, v33, v26, v27
	s_nop 0
	v_max3_f32 v32, v32, v24, v25
	v_max3_f32 v33, v33, v10, v11
	s_nop 0
	v_max3_f32 v32, v32, v8, v9
	v_max3_f32 v33, v33, v30, v31
	s_nop 0
	v_max3_f32 v32, v32, v28, v29
	v_max3_f32 v33, v33, v14, v15
	s_nop 0
	v_max3_f32 v32, v32, v12, v13
	s_nop 0
	v_max_f32_e32 v32, v32, v33
	s_nop 0
	v_mov_b32_e32 v33, v32
	s_nop 1
	v_permlane32_swap_b32_e32 v32, v33
	v_max_f32_e32 v32, v32, v33
	s_nop 0
	v_sub_f32_e32 v0, v0, v32
	v_sub_f32_e32 v1, v1, v32
	v_sub_f32_e32 v16, v16, v32
	v_sub_f32_e32 v17, v17, v32
	v_sub_f32_e32 v18, v18, v32
	v_sub_f32_e32 v2, v2, v32
	s_nop 0
	v_exp_f32_e32 v64, v0
	v_exp_f32_e32 v65, v1
	v_lshl_add_u64 v[0:1], v[188:189], 0, s[58:59]
	s_mov_b32 s0, m0
	s_mov_b32 m0, s64
	s_nop 0
	global_load_lds_dwordx4 v[0:1], off
	s_mov_b32 m0, s0
	s_cselect_b32 s0, 0, 0
	s_add_i32 s24, s0, s63
	v_lshl_add_u64 v[0:1], v[190:191], 0, s[82:83]
	s_add_i32 s0, s24, 0xa000
	s_mov_b32 s1, m0
	s_mov_b32 m0, s0
	s_nop 0
	global_load_lds_dwordx4 v[0:1], off
	s_mov_b32 m0, s1
	s_mov_b64 s[0:1], 0x20080
	v_lshl_add_u64 v[0:1], v[190:191], 0, s[0:1]
	s_add_i32 s24, s24, 0xc000
	s_mov_b32 s0, m0
	s_mov_b32 m0, s24
	s_nop 0
	global_load_lds_dwordx4 v[0:1], off
	s_mov_b32 m0, s0
	ds_read_b128 v[172:175], v208 offset:8192
	ds_read_b128 v[160:163], v208 offset:8704
	ds_read_b128 v[168:171], v208 offset:10240
	ds_read_b128 v[152:155], v208 offset:10752
	ds_read_b128 v[164:167], v208 offset:12288
	ds_read_b128 v[148:151], v208 offset:12800
	ds_read_b128 v[156:159], v208 offset:14336
	ds_read_b128 v[144:147], v208 offset:14848
	v_sub_f32_e32 v19, v19, v32
	v_sub_f32_e32 v3, v3, v32
	v_sub_f32_e32 v20, v20, v32
	v_sub_f32_e32 v4, v4, v32
	v_sub_f32_e32 v21, v21, v32
	v_sub_f32_e32 v5, v5, v32
	v_sub_f32_e32 v22, v22, v32
	v_sub_f32_e32 v6, v6, v32
	v_sub_f32_e32 v23, v23, v32
	v_sub_f32_e32 v7, v7, v32
	v_sub_f32_e32 v24, v24, v32
	v_sub_f32_e32 v8, v8, v32
	v_sub_f32_e32 v25, v25, v32
	v_sub_f32_e32 v9, v9, v32
	v_sub_f32_e32 v26, v26, v32
	v_sub_f32_e32 v10, v10, v32
	v_sub_f32_e32 v27, v27, v32
	v_sub_f32_e32 v11, v11, v32
	v_sub_f32_e32 v28, v28, v32
	v_sub_f32_e32 v12, v12, v32
	v_sub_f32_e32 v29, v29, v32
	v_sub_f32_e32 v13, v13, v32
	v_sub_f32_e32 v30, v30, v32
	v_sub_f32_e32 v14, v14, v32
	v_sub_f32_e32 v31, v31, v32
	v_sub_f32_e32 v15, v15, v32
	v_exp_f32_e32 v80, v16
	v_exp_f32_e32 v81, v17
	v_exp_f32_e32 v82, v18
	v_exp_f32_e32 v83, v19
	v_exp_f32_e32 v84, v20
	v_exp_f32_e32 v85, v21
	v_exp_f32_e32 v86, v22
	v_exp_f32_e32 v87, v23
	v_exp_f32_e32 v88, v24
	v_exp_f32_e32 v89, v25
	v_exp_f32_e32 v90, v26
	v_exp_f32_e32 v91, v27
	v_exp_f32_e32 v92, v28
	v_exp_f32_e32 v93, v29
	v_exp_f32_e32 v94, v30
	v_exp_f32_e32 v95, v31
	v_exp_f32_e32 v66, v2
	v_exp_f32_e32 v67, v3
	v_exp_f32_e32 v68, v4
	v_exp_f32_e32 v69, v5
	v_exp_f32_e32 v70, v6
	v_exp_f32_e32 v71, v7
	v_exp_f32_e32 v72, v8
	v_exp_f32_e32 v73, v9
	v_exp_f32_e32 v74, v10
	v_exp_f32_e32 v75, v11
	v_exp_f32_e32 v76, v12
	v_exp_f32_e32 v77, v13
	v_exp_f32_e32 v78, v14
	v_exp_f32_e32 v79, v15
	s_waitcnt vmcnt(3) lgkmcnt(0)
	s_barrier
	s_cmp_lt_i32 s17, 7
	v_cmp_gt_u32_e64 s[0:1], 32, v202
	v_add_f32_e32 v211, v179, v32
	s_cbranch_scc1 .LBB5_836
	v_mov_b32_e32 v16, v179
	v_mov_b32_e32 v17, v179
	v_mov_b32_e32 v30, v179
	v_mov_b32_e32 v31, v179
	s_mov_b64 s[12:13], 0xa0000
	v_mov_b32_e32 v18, v179
	v_mov_b32_e32 v19, v179
	v_mov_b32_e32 v20, v179
	v_mov_b32_e32 v21, v179
	v_mov_b32_e32 v22, v179
	v_mov_b32_e32 v23, v179
	v_mov_b32_e32 v24, v179
	v_mov_b32_e32 v25, v179
	v_mov_b32_e32 v26, v179
	v_mov_b32_e32 v27, v179
	v_mov_b32_e32 v28, v179
	v_mov_b32_e32 v29, v179
	v_mov_b64_e32 v[62:63], v[30:31]
	v_mov_b64_e32 v[46:47], v[30:31]
	v_mov_b64_e32 v[0:1], v[16:17]
	s_add_i32 s30, s17, -5
	v_lshl_add_u64 v[194:195], v[192:193], 0, s[58:59]
	v_lshl_add_u64 v[196:197], v[190:191], 0, s[58:59]
	v_lshl_add_u64 v[198:199], v[188:189], 0, s[12:13]
	s_mov_b32 s34, 0
	s_movk_i32 s3, 0x4000
	s_movk_i32 s33, 0x2000
	v_mov_b32_e32 v214, 0
	v_mov_b64_e32 v[60:61], v[28:29]
	v_mov_b64_e32 v[58:59], v[26:27]
	v_mov_b64_e32 v[56:57], v[24:25]
	v_mov_b64_e32 v[54:55], v[22:23]
	v_mov_b64_e32 v[52:53], v[20:21]
	v_mov_b64_e32 v[50:51], v[18:19]
	v_mov_b64_e32 v[48:49], v[16:17]
	v_mov_b64_e32 v[44:45], v[28:29]
	v_mov_b64_e32 v[42:43], v[26:27]
	v_mov_b64_e32 v[40:41], v[24:25]
	v_mov_b64_e32 v[38:39], v[22:23]
	v_mov_b64_e32 v[36:37], v[20:21]
	v_mov_b64_e32 v[34:35], v[18:19]
	v_mov_b64_e32 v[32:33], v[16:17]
	v_mov_b64_e32 v[2:3], v[18:19]
	v_mov_b64_e32 v[4:5], v[20:21]
	v_mov_b64_e32 v[6:7], v[22:23]
	v_mov_b64_e32 v[8:9], v[24:25]
	v_mov_b64_e32 v[10:11], v[26:27]
	v_mov_b64_e32 v[12:13], v[28:29]
	v_mov_b64_e32 v[14:15], v[30:31]
	s_mov_b32 s32, m0
	v_xor_b32_e32 v220, 0x80000000, v211
	v_mov_b32_e32 v221, v220
	v_mov_b32_e32 v222, v220
	v_mov_b32_e32 v223, v220
	v_mov_b32_e32 v224, v220
	v_mov_b32_e32 v225, v220
	v_mov_b32_e32 v226, v220
	v_mov_b32_e32 v227, v220
	v_mov_b32_e32 v228, v220
	v_mov_b32_e32 v229, v220
	v_mov_b32_e32 v230, v220
	v_mov_b32_e32 v231, v220
	v_mov_b32_e32 v232, v220
	v_mov_b32_e32 v233, v220
	v_mov_b32_e32 v234, v220
	v_mov_b32_e32 v235, v220
	ds_read_b128 v[236:239], v207
	ds_read_b128 v[240:243], v207 offset:1024
	ds_read_b128 v[244:247], v207 offset:2048
	ds_read_b128 v[252:255], v207 offset:3072
	s_waitcnt lgkmcnt(0)
.LBB5_822:
	s_lshl_b32 s24, s34, 1
	v_add_u32_e32 v183, s24, v212
	v_add_u32_e32 v215, s3, v208
	v_add_f32_e32 v251, v80, v81
	v_mfma_f32_32x32x16_bf16 v[112:127], v[172:175], v[236:239], v[220:235]
	v_lshl_add_u64 v[248:249], v[198:199], 0, s[36:37]
	s_add_i32 s24, s33, s64
	s_mov_b32 m0, s24
	s_nop 0
	global_load_lds_dwordx4 v[248:249], off
	v_add_f32_e32 v251, v82, v251
	v_add_f32_e32 v251, v83, v251
	v_add_f32_e32 v251, v84, v251
	v_add_f32_e32 v251, v85, v251
	v_cvt_pk_bf16_f32 v140, v80, v81
	v_cvt_pk_bf16_f32 v141, v82, v83
	ds_read_b128 v[172:175], v215
	v_mfma_f32_32x32x16_bf16 v[96:111], v[160:163], v[236:239], v[220:235]
	v_lshl_add_u64 v[248:249], v[196:197], 0, s[36:37]
	s_lshl_b32 s24, s3, 1
	s_add_i32 s24, s24, s66
	s_mov_b32 m0, s24
	s_nop 0
	global_load_lds_dwordx4 v[248:249], off
	v_add_f32_e32 v251, v86, v251
	v_add_f32_e32 v251, v87, v251
	v_add_f32_e32 v251, v88, v251
	v_add_f32_e32 v251, v89, v251
	v_cvt_pk_bf16_f32 v142, v84, v85
	v_cvt_pk_bf16_f32 v143, v86, v87
	ds_read_b128 v[160:163], v215 offset:512
	v_mfma_f32_32x32x16_bf16 v[112:127], v[168:171], v[240:243], v[112:127]
	v_lshl_add_u64 v[248:249], v[194:195], 0, s[36:37]
	s_addk_i32 s24, 0x2000
	s_mov_b32 m0, s24
	s_nop 0
	global_load_lds_dwordx4 v[248:249], off
	v_add_f32_e32 v251, v90, v251
	v_add_f32_e32 v251, v91, v251
	v_add_f32_e32 v251, v92, v251
	v_add_f32_e32 v251, v93, v251
	v_cvt_pk_bf16_f32 v136, v88, v89
	v_cvt_pk_bf16_f32 v137, v90, v91
	ds_read_b128 v[168:171], v215 offset:2048
	v_mfma_f32_32x32x16_bf16 v[96:111], v[152:155], v[240:243], v[96:111]
	v_add_f32_e32 v251, v94, v251
	v_add_f32_e32 v251, v95, v251
	v_add_f32_e32 v251, v64, v251
	v_add_f32_e32 v251, v65, v251
	v_cvt_pk_bf16_f32 v138, v92, v93
	v_cvt_pk_bf16_f32 v139, v94, v95
	ds_read_b128 v[152:155], v215 offset:2560
	v_mfma_f32_32x32x16_bf16 v[112:127], v[164:167], v[244:247], v[112:127]
	v_add_f32_e32 v251, v66, v251
	v_add_f32_e32 v251, v67, v251
	v_add_f32_e32 v251, v68, v251
	v_add_f32_e32 v251, v69, v251
	v_cvt_pk_bf16_f32 v132, v64, v65
	v_cvt_pk_bf16_f32 v133, v66, v67
	ds_read_b128 v[164:167], v215 offset:4096
	v_mfma_f32_32x32x16_bf16 v[96:111], v[148:151], v[244:247], v[96:111]
	v_add_f32_e32 v251, v70, v251
	v_add_f32_e32 v251, v71, v251
	v_add_f32_e32 v251, v72, v251
	v_add_f32_e32 v251, v73, v251
	v_cvt_pk_bf16_f32 v134, v68, v69
	v_cvt_pk_bf16_f32 v135, v70, v71
	ds_read_b128 v[148:151], v215 offset:4608
	ds_read_b64_tr_b16 v[80:81], v183 offset:24576
	ds_read_b64_tr_b16 v[82:83], v183 offset:25088
	v_mfma_f32_32x32x16_bf16 v[112:127], v[156:159], v[252:255], v[112:127]
	v_add_f32_e32 v251, v74, v251
	v_add_f32_e32 v251, v75, v251
	v_add_f32_e32 v251, v76, v251
	v_add_f32_e32 v251, v77, v251
	v_cvt_pk_bf16_f32 v128, v72, v73
	v_cvt_pk_bf16_f32 v129, v74, v75
	ds_read_b128 v[156:159], v215 offset:6144
	ds_read_b64_tr_b16 v[84:85], v183 offset:28672
	ds_read_b64_tr_b16 v[86:87], v183 offset:29184
	v_mfma_f32_32x32x16_bf16 v[96:111], v[144:147], v[252:255], v[96:111]
	v_add_f32_e32 v251, v78, v251
	v_add_f32_e32 v251, v79, v251
	v_cvt_pk_bf16_f32 v130, v76, v77
	v_cvt_pk_bf16_f32 v131, v78, v79
	ds_read_b128 v[144:147], v215 offset:6656
	ds_read_b64_tr_b16 v[88:89], v183 offset:32768
	ds_read_b64_tr_b16 v[90:91], v183 offset:33280
	s_waitcnt lgkmcnt(6)
	v_mfma_f32_32x32x16_bf16 v[16:31], v[140:143], v[80:83], v[16:31]
	ds_read_b64_tr_b16 v[92:93], v183 offset:36864
	ds_read_b64_tr_b16 v[94:95], v183 offset:37376
	v_max3_f32 v76, v112, v113, v114
	v_max3_f32 v76, v76, v115, v116
	v_max3_f32 v76, v76, v117, v118
	v_max3_f32 v76, v76, v119, v120
	v_max3_f32 v76, v76, v121, v122
	v_max3_f32 v76, v76, v123, v124
	s_waitcnt lgkmcnt(5)
	v_mfma_f32_32x32x16_bf16 v[48:63], v[140:143], v[84:87], v[48:63]
	ds_read_b64_tr_b16 v[64:65], v183 offset:25600
	ds_read_b64_tr_b16 v[66:67], v183 offset:26112
	v_max3_f32 v76, v76, v125, v126
	v_max3_f32 v76, v76, v127, v127
	v_max3_f32 v77, v96, v97, v98
	v_max3_f32 v77, v77, v99, v100
	v_max3_f32 v77, v77, v101, v102
	v_max3_f32 v77, v77, v103, v104
	s_waitcnt lgkmcnt(4)
	v_mfma_f32_32x32x16_bf16 v[32:47], v[140:143], v[88:91], v[32:47]
	ds_read_b64_tr_b16 v[68:69], v183 offset:29696
	ds_read_b64_tr_b16 v[70:71], v183 offset:30208
	v_max3_f32 v77, v77, v105, v106
	v_max3_f32 v77, v77, v107, v108
	v_max3_f32 v77, v77, v109, v110
	v_max3_f32 v77, v77, v111, v111
	v_max_f32_e32 v76, v76, v77
	v_mov_b32_e32 v77, v76
	s_waitcnt lgkmcnt(4)
	v_mfma_f32_32x32x16_bf16 v[0:15], v[140:143], v[92:95], v[0:15]
	ds_read_b64_tr_b16 v[80:81], v183 offset:33792
	ds_read_b64_tr_b16 v[82:83], v183 offset:34304
	s_nop 1
	v_permlane32_swap_b32_e32 v76, v77
	v_max_f32_e32 v77, v77, v77
	v_max_f32_e32 v76, v76, v76
	v_max_f32_e32 v76, v76, v77
	v_cmp_lt_f32_e32 vcc, s85, v76
	s_cmp_lg_u64 vcc, 0
	v_add_f32_e32 v214, v214, v251
	s_cselect_b64 s[46:47], -1, 0
	s_cbranch_vccnz .LBB5_830
.LBB5_823:
	s_waitcnt lgkmcnt(4)
	v_mfma_f32_32x32x16_bf16 v[16:31], v[136:139], v[64:67], v[16:31]
	ds_read_b64_tr_b16 v[84:85], v183 offset:37888
	ds_read_b64_tr_b16 v[86:87], v183 offset:38400
	v_exp_f32_e32 v112, v112
	v_exp_f32_e32 v113, v113
	v_exp_f32_e32 v114, v114
	s_waitcnt lgkmcnt(4)
	v_mfma_f32_32x32x16_bf16 v[48:63], v[136:139], v[68:71], v[48:63]
	ds_read_b64_tr_b16 v[88:89], v183 offset:26624
	ds_read_b64_tr_b16 v[90:91], v183 offset:27136
	v_exp_f32_e32 v115, v115
	v_exp_f32_e32 v116, v116
	v_exp_f32_e32 v117, v117
	s_waitcnt lgkmcnt(4)
	v_mfma_f32_32x32x16_bf16 v[32:47], v[136:139], v[80:83], v[32:47]
	ds_read_b64_tr_b16 v[92:93], v183 offset:30720
	ds_read_b64_tr_b16 v[94:95], v183 offset:31232
	v_exp_f32_e32 v118, v118
	v_exp_f32_e32 v119, v119
	v_exp_f32_e32 v120, v120
	s_waitcnt lgkmcnt(4)
	v_mfma_f32_32x32x16_bf16 v[0:15], v[136:139], v[84:87], v[0:15]
	ds_read_b64_tr_b16 v[64:65], v183 offset:34816
	ds_read_b64_tr_b16 v[66:67], v183 offset:35328
	v_exp_f32_e32 v121, v121
	v_exp_f32_e32 v122, v122
	v_exp_f32_e32 v123, v123
	s_waitcnt lgkmcnt(4)
	v_mfma_f32_32x32x16_bf16 v[16:31], v[132:135], v[88:91], v[16:31]
	ds_read_b64_tr_b16 v[68:69], v183 offset:38912
	ds_read_b64_tr_b16 v[70:71], v183 offset:39424
	v_exp_f32_e32 v124, v124
	v_exp_f32_e32 v125, v125
	v_exp_f32_e32 v126, v126
	s_waitcnt lgkmcnt(4)
	v_mfma_f32_32x32x16_bf16 v[48:63], v[132:135], v[92:95], v[48:63]
	ds_read_b64_tr_b16 v[80:81], v183 offset:27648
	ds_read_b64_tr_b16 v[82:83], v183 offset:28160
	v_exp_f32_e32 v127, v127
	v_exp_f32_e32 v96, v96
	v_exp_f32_e32 v97, v97
	s_waitcnt lgkmcnt(4)
	v_mfma_f32_32x32x16_bf16 v[32:47], v[132:135], v[64:67], v[32:47]
	ds_read_b64_tr_b16 v[84:85], v183 offset:31744
	ds_read_b64_tr_b16 v[86:87], v183 offset:32256
	v_exp_f32_e32 v98, v98
	v_exp_f32_e32 v99, v99
	v_exp_f32_e32 v100, v100
	s_waitcnt lgkmcnt(4)
	v_mfma_f32_32x32x16_bf16 v[0:15], v[132:135], v[68:71], v[0:15]
	ds_read_b64_tr_b16 v[88:89], v183 offset:35840
	ds_read_b64_tr_b16 v[90:91], v183 offset:36352
	v_exp_f32_e32 v101, v101
	v_exp_f32_e32 v102, v102
	v_exp_f32_e32 v103, v103
	s_waitcnt lgkmcnt(4)
	v_mfma_f32_32x32x16_bf16 v[16:31], v[128:131], v[80:83], v[16:31]
	ds_read_b64_tr_b16 v[92:93], v183 offset:39936
	ds_read_b64_tr_b16 v[94:95], v183 offset:40448
	v_exp_f32_e32 v104, v104
	v_exp_f32_e32 v105, v105
	s_waitcnt lgkmcnt(4)
	v_mfma_f32_32x32x16_bf16 v[48:63], v[128:131], v[84:87], v[48:63]
	v_exp_f32_e32 v106, v106
	v_exp_f32_e32 v107, v107
	s_waitcnt lgkmcnt(2)
	v_mfma_f32_32x32x16_bf16 v[32:47], v[128:131], v[88:91], v[32:47]
	v_exp_f32_e32 v108, v108
	v_exp_f32_e32 v109, v109
	s_waitcnt lgkmcnt(0)
	v_mfma_f32_32x32x16_bf16 v[0:15], v[128:131], v[92:95], v[0:15]
	v_exp_f32_e32 v110, v110
	v_exp_f32_e32 v111, v111
	s_waitcnt vmcnt(3) lgkmcnt(0)
	s_barrier
	s_andn2_b64 vcc, exec, s[46:47]
	v_add_u32_e32 v183, s80, v184
	s_cbranch_vccnz .LBB5_825
	s_waitcnt lgkmcnt(0)
	ds_read_b128 v[72:75], v183 offset:96
	ds_read_b128 v[76:79], v183 offset:64
	ds_read_b128 v[80:83], v183 offset:32
	ds_read_b128 v[84:87], v183
	s_waitcnt lgkmcnt(3)
	v_pk_mul_f32 v[28:29], v[28:29], v[72:73]
	s_waitcnt lgkmcnt(2)
	v_pk_mul_f32 v[24:25], v[24:25], v[76:77]
	s_waitcnt lgkmcnt(1)
	v_pk_mul_f32 v[20:21], v[20:21], v[80:81]
	v_pk_mul_f32 v[30:31], v[30:31], v[74:75]
	v_pk_mul_f32 v[26:27], v[26:27], v[78:79]
	v_pk_mul_f32 v[22:23], v[22:23], v[82:83]
	s_waitcnt lgkmcnt(0)
	v_pk_mul_f32 v[18:19], v[18:19], v[86:87]
	v_pk_mul_f32 v[16:17], v[16:17], v[84:85]
	v_pk_mul_f32 v[60:61], v[60:61], v[72:73]
	v_pk_mul_f32 v[56:57], v[56:57], v[76:77]
	v_pk_mul_f32 v[52:53], v[52:53], v[80:81]
	v_pk_mul_f32 v[62:63], v[62:63], v[74:75]
	v_pk_mul_f32 v[58:59], v[58:59], v[78:79]
	v_pk_mul_f32 v[54:55], v[54:55], v[82:83]
	v_pk_mul_f32 v[50:51], v[50:51], v[86:87]
	v_pk_mul_f32 v[48:49], v[48:49], v[84:85]
	v_pk_mul_f32 v[44:45], v[44:45], v[72:73]
	v_pk_mul_f32 v[40:41], v[40:41], v[76:77]
	v_pk_mul_f32 v[36:37], v[36:37], v[80:81]
	v_pk_mul_f32 v[46:47], v[46:47], v[74:75]
	v_pk_mul_f32 v[42:43], v[42:43], v[78:79]
	v_pk_mul_f32 v[38:39], v[38:39], v[82:83]
	v_pk_mul_f32 v[34:35], v[34:35], v[86:87]
	v_pk_mul_f32 v[32:33], v[32:33], v[84:85]
	v_pk_mul_f32 v[12:13], v[12:13], v[72:73]
	v_pk_mul_f32 v[8:9], v[8:9], v[76:77]
	v_pk_mul_f32 v[4:5], v[4:5], v[80:81]
	v_pk_mul_f32 v[14:15], v[14:15], v[74:75]
	v_pk_mul_f32 v[10:11], v[10:11], v[78:79]
	v_pk_mul_f32 v[6:7], v[6:7], v[82:83]
	v_pk_mul_f32 v[2:3], v[2:3], v[86:87]
	v_pk_mul_f32 v[0:1], v[0:1], v[84:85]
.LBB5_825:
	s_add_i32 s24, s3, 0x2000
	s_cmpk_lg_i32 s3, 0x4000
	s_cselect_b32 s25, s24, 0
	s_lshl_b32 s24, s33, 1
	v_add_u32_e32 v213, s24, v212
	v_add_u32_e32 v215, s25, v208
	v_add_f32_e32 v251, v112, v113
	v_mfma_f32_32x32x16_bf16 v[80:95], v[172:175], v[236:239], v[220:235]
	s_add_i32 s24, s3, s64
	s_mov_b32 m0, s24
	s_nop 0
	global_load_lds_dwordx4 v[198:199], off
	v_add_f32_e32 v251, v114, v251
	v_add_f32_e32 v251, v115, v251
	v_add_f32_e32 v251, v116, v251
	v_add_f32_e32 v251, v117, v251
	v_cvt_pk_bf16_f32 v140, v112, v113
	v_cvt_pk_bf16_f32 v141, v114, v115
	ds_read_b128 v[172:175], v215
	v_mfma_f32_32x32x16_bf16 v[64:79], v[160:163], v[236:239], v[220:235]
	s_lshl_b32 s24, s25, 1
	s_add_i32 s24, s24, s66
	s_mov_b32 m0, s24
	s_nop 0
	global_load_lds_dwordx4 v[196:197], off
	v_add_f32_e32 v251, v118, v251
	v_add_f32_e32 v251, v119, v251
	v_add_f32_e32 v251, v120, v251
	v_add_f32_e32 v251, v121, v251
	v_cvt_pk_bf16_f32 v142, v116, v117
	v_cvt_pk_bf16_f32 v143, v118, v119
	ds_read_b128 v[160:163], v215 offset:512
	v_mfma_f32_32x32x16_bf16 v[80:95], v[168:171], v[240:243], v[80:95]
	s_addk_i32 s24, 0x2000
	s_mov_b32 m0, s24
	s_nop 0
	global_load_lds_dwordx4 v[194:195], off
	v_add_f32_e32 v251, v122, v251
	v_add_f32_e32 v251, v123, v251
	v_add_f32_e32 v251, v124, v251
	v_add_f32_e32 v251, v125, v251
	v_cvt_pk_bf16_f32 v136, v120, v121
	v_cvt_pk_bf16_f32 v137, v122, v123
	ds_read_b128 v[168:171], v215 offset:2048
	v_mfma_f32_32x32x16_bf16 v[64:79], v[152:155], v[240:243], v[64:79]
	v_add_f32_e32 v251, v126, v251
	v_add_f32_e32 v251, v127, v251
	v_add_f32_e32 v251, v96, v251
	v_add_f32_e32 v251, v97, v251
	v_cvt_pk_bf16_f32 v138, v124, v125
	v_cvt_pk_bf16_f32 v139, v126, v127
	ds_read_b128 v[152:155], v215 offset:2560
	v_mfma_f32_32x32x16_bf16 v[80:95], v[164:167], v[244:247], v[80:95]
	v_add_f32_e32 v251, v98, v251
	v_add_f32_e32 v251, v99, v251
	v_add_f32_e32 v251, v100, v251
	v_add_f32_e32 v251, v101, v251
	v_cvt_pk_bf16_f32 v132, v96, v97
	v_cvt_pk_bf16_f32 v133, v98, v99
	ds_read_b128 v[164:167], v215 offset:4096
	v_mfma_f32_32x32x16_bf16 v[64:79], v[148:151], v[244:247], v[64:79]
	v_add_f32_e32 v251, v102, v251
	v_add_f32_e32 v251, v103, v251
	v_add_f32_e32 v251, v104, v251
	v_add_f32_e32 v251, v105, v251
	v_cvt_pk_bf16_f32 v134, v100, v101
	v_cvt_pk_bf16_f32 v135, v102, v103
	ds_read_b128 v[148:151], v215 offset:4608
	ds_read_b64_tr_b16 v[112:113], v213 offset:24576
	ds_read_b64_tr_b16 v[114:115], v213 offset:25088
	v_mfma_f32_32x32x16_bf16 v[80:95], v[156:159], v[252:255], v[80:95]
	v_add_f32_e32 v251, v106, v251
	v_add_f32_e32 v251, v107, v251
	v_add_f32_e32 v251, v108, v251
	v_add_f32_e32 v251, v109, v251
	v_cvt_pk_bf16_f32 v128, v104, v105
	v_cvt_pk_bf16_f32 v129, v106, v107
	ds_read_b128 v[156:159], v215 offset:6144
	ds_read_b64_tr_b16 v[116:117], v213 offset:28672
	ds_read_b64_tr_b16 v[118:119], v213 offset:29184
	v_mfma_f32_32x32x16_bf16 v[64:79], v[144:147], v[252:255], v[64:79]
	v_add_f32_e32 v251, v110, v251
	v_add_f32_e32 v251, v111, v251
	v_cvt_pk_bf16_f32 v130, v108, v109
	v_cvt_pk_bf16_f32 v131, v110, v111
	ds_read_b128 v[144:147], v215 offset:6656
	ds_read_b64_tr_b16 v[120:121], v213 offset:32768
	ds_read_b64_tr_b16 v[122:123], v213 offset:33280
	s_waitcnt lgkmcnt(6)
	v_mfma_f32_32x32x16_bf16 v[16:31], v[140:143], v[112:115], v[16:31]
	ds_read_b64_tr_b16 v[124:125], v213 offset:36864
	ds_read_b64_tr_b16 v[126:127], v213 offset:37376
	v_max3_f32 v108, v80, v81, v82
	v_max3_f32 v108, v108, v83, v84
	v_max3_f32 v108, v108, v85, v86
	v_max3_f32 v108, v108, v87, v88
	v_max3_f32 v108, v108, v89, v90
	v_max3_f32 v108, v108, v91, v92
	s_waitcnt lgkmcnt(5)
	v_mfma_f32_32x32x16_bf16 v[48:63], v[140:143], v[116:119], v[48:63]
	ds_read_b64_tr_b16 v[96:97], v213 offset:25600
	ds_read_b64_tr_b16 v[98:99], v213 offset:26112
	v_max3_f32 v108, v108, v93, v94
	v_max3_f32 v108, v108, v95, v95
	v_max3_f32 v109, v64, v65, v66
	v_max3_f32 v109, v109, v67, v68
	v_max3_f32 v109, v109, v69, v70
	v_max3_f32 v109, v109, v71, v72
	s_waitcnt lgkmcnt(4)
	v_mfma_f32_32x32x16_bf16 v[32:47], v[140:143], v[120:123], v[32:47]
	ds_read_b64_tr_b16 v[100:101], v213 offset:29696
	ds_read_b64_tr_b16 v[102:103], v213 offset:30208
	v_max3_f32 v109, v109, v73, v74
	v_max3_f32 v109, v109, v75, v76
	v_max3_f32 v109, v109, v77, v78
	v_max3_f32 v109, v109, v79, v79
	v_max_f32_e32 v108, v108, v109
	v_mov_b32_e32 v109, v108
	s_waitcnt lgkmcnt(4)
	v_mfma_f32_32x32x16_bf16 v[0:15], v[140:143], v[124:127], v[0:15]
	ds_read_b64_tr_b16 v[112:113], v213 offset:33792
	ds_read_b64_tr_b16 v[114:115], v213 offset:34304
	s_nop 1
	v_permlane32_swap_b32_e32 v108, v109
	v_max_f32_e32 v109, v109, v109
	v_max_f32_e32 v108, v108, v108
	v_max_f32_e32 v108, v108, v109
	v_cmp_lt_f32_e32 vcc, s85, v108
	s_cmp_lg_u64 vcc, 0
	v_add_f32_e32 v214, v214, v251
	s_cselect_b64 s[46:47], -1, 0
	s_cbranch_vccnz .LBB5_833
.LBB5_826:
	s_waitcnt lgkmcnt(4)
	v_mfma_f32_32x32x16_bf16 v[16:31], v[136:139], v[96:99], v[16:31]
	ds_read_b64_tr_b16 v[116:117], v213 offset:37888
	ds_read_b64_tr_b16 v[118:119], v213 offset:38400
	v_exp_f32_e32 v80, v80
	v_exp_f32_e32 v81, v81
	v_exp_f32_e32 v82, v82
	s_waitcnt lgkmcnt(4)
	v_mfma_f32_32x32x16_bf16 v[48:63], v[136:139], v[100:103], v[48:63]
	ds_read_b64_tr_b16 v[120:121], v213 offset:26624
	ds_read_b64_tr_b16 v[122:123], v213 offset:27136
	v_exp_f32_e32 v83, v83
	v_exp_f32_e32 v84, v84
	v_exp_f32_e32 v85, v85
	s_waitcnt lgkmcnt(4)
	v_mfma_f32_32x32x16_bf16 v[32:47], v[136:139], v[112:115], v[32:47]
	ds_read_b64_tr_b16 v[124:125], v213 offset:30720
	ds_read_b64_tr_b16 v[126:127], v213 offset:31232
	v_exp_f32_e32 v86, v86
	v_exp_f32_e32 v87, v87
	v_exp_f32_e32 v88, v88
	s_waitcnt lgkmcnt(4)
	v_mfma_f32_32x32x16_bf16 v[0:15], v[136:139], v[116:119], v[0:15]
	ds_read_b64_tr_b16 v[96:97], v213 offset:34816
	ds_read_b64_tr_b16 v[98:99], v213 offset:35328
	v_exp_f32_e32 v89, v89
	v_exp_f32_e32 v90, v90
	v_exp_f32_e32 v91, v91
	s_waitcnt lgkmcnt(4)
	v_mfma_f32_32x32x16_bf16 v[16:31], v[132:135], v[120:123], v[16:31]
	ds_read_b64_tr_b16 v[100:101], v213 offset:38912
	ds_read_b64_tr_b16 v[102:103], v213 offset:39424
	v_exp_f32_e32 v92, v92
	v_exp_f32_e32 v93, v93
	v_exp_f32_e32 v94, v94
	s_waitcnt lgkmcnt(4)
	v_mfma_f32_32x32x16_bf16 v[48:63], v[132:135], v[124:127], v[48:63]
	ds_read_b64_tr_b16 v[112:113], v213 offset:27648
	ds_read_b64_tr_b16 v[114:115], v213 offset:28160
	v_exp_f32_e32 v95, v95
	v_exp_f32_e32 v64, v64
	v_exp_f32_e32 v65, v65
	s_waitcnt lgkmcnt(4)
	v_mfma_f32_32x32x16_bf16 v[32:47], v[132:135], v[96:99], v[32:47]
	ds_read_b64_tr_b16 v[116:117], v213 offset:31744
	ds_read_b64_tr_b16 v[118:119], v213 offset:32256
	v_exp_f32_e32 v66, v66
	v_exp_f32_e32 v67, v67
	v_exp_f32_e32 v68, v68
	s_waitcnt lgkmcnt(4)
	v_mfma_f32_32x32x16_bf16 v[0:15], v[132:135], v[100:103], v[0:15]
	ds_read_b64_tr_b16 v[120:121], v213 offset:35840
	ds_read_b64_tr_b16 v[122:123], v213 offset:36352
	v_exp_f32_e32 v69, v69
	v_exp_f32_e32 v70, v70
	v_exp_f32_e32 v71, v71
	s_waitcnt lgkmcnt(4)
	v_mfma_f32_32x32x16_bf16 v[16:31], v[128:131], v[112:115], v[16:31]
	ds_read_b64_tr_b16 v[124:125], v213 offset:39936
	ds_read_b64_tr_b16 v[126:127], v213 offset:40448
	v_exp_f32_e32 v72, v72
	v_exp_f32_e32 v73, v73
	s_waitcnt lgkmcnt(4)
	v_mfma_f32_32x32x16_bf16 v[48:63], v[128:131], v[116:119], v[48:63]
	v_exp_f32_e32 v74, v74
	v_exp_f32_e32 v75, v75
	s_waitcnt lgkmcnt(2)
	v_mfma_f32_32x32x16_bf16 v[32:47], v[128:131], v[120:123], v[32:47]
	v_exp_f32_e32 v76, v76
	v_exp_f32_e32 v77, v77
	s_waitcnt lgkmcnt(0)
	v_mfma_f32_32x32x16_bf16 v[0:15], v[128:131], v[124:127], v[0:15]
	v_exp_f32_e32 v78, v78
	v_exp_f32_e32 v79, v79
	s_waitcnt vmcnt(3) lgkmcnt(0)
	s_barrier
	s_andn2_b64 vcc, exec, s[46:47]
	s_cbranch_vccnz .LBB5_828
	s_waitcnt lgkmcnt(0)
	ds_read_b128 v[96:99], v183 offset:96
	ds_read_b128 v[100:103], v183 offset:64
	ds_read_b128 v[104:107], v183 offset:32
	ds_read_b128 v[108:111], v183
	s_waitcnt lgkmcnt(3)
	v_pk_mul_f32 v[28:29], v[28:29], v[96:97]
	s_waitcnt lgkmcnt(2)
	v_pk_mul_f32 v[24:25], v[24:25], v[100:101]
	s_waitcnt lgkmcnt(1)
	v_pk_mul_f32 v[20:21], v[20:21], v[104:105]
	v_pk_mul_f32 v[30:31], v[30:31], v[98:99]
	v_pk_mul_f32 v[26:27], v[26:27], v[102:103]
	v_pk_mul_f32 v[22:23], v[22:23], v[106:107]
	s_waitcnt lgkmcnt(0)
	v_pk_mul_f32 v[18:19], v[18:19], v[110:111]
	v_pk_mul_f32 v[16:17], v[16:17], v[108:109]
	v_pk_mul_f32 v[60:61], v[60:61], v[96:97]
	v_pk_mul_f32 v[56:57], v[56:57], v[100:101]
	v_pk_mul_f32 v[52:53], v[52:53], v[104:105]
	v_pk_mul_f32 v[62:63], v[62:63], v[98:99]
	v_pk_mul_f32 v[58:59], v[58:59], v[102:103]
	v_pk_mul_f32 v[54:55], v[54:55], v[106:107]
	v_pk_mul_f32 v[50:51], v[50:51], v[110:111]
	v_pk_mul_f32 v[48:49], v[48:49], v[108:109]
	v_pk_mul_f32 v[44:45], v[44:45], v[96:97]
	v_pk_mul_f32 v[40:41], v[40:41], v[100:101]
	v_pk_mul_f32 v[36:37], v[36:37], v[104:105]
	v_pk_mul_f32 v[46:47], v[46:47], v[98:99]
	v_pk_mul_f32 v[42:43], v[42:43], v[102:103]
	v_pk_mul_f32 v[38:39], v[38:39], v[106:107]
	v_pk_mul_f32 v[34:35], v[34:35], v[110:111]
	v_pk_mul_f32 v[32:33], v[32:33], v[108:109]
	v_pk_mul_f32 v[12:13], v[12:13], v[96:97]
	v_pk_mul_f32 v[8:9], v[8:9], v[100:101]
	v_pk_mul_f32 v[4:5], v[4:5], v[104:105]
	v_pk_mul_f32 v[14:15], v[14:15], v[98:99]
	v_pk_mul_f32 v[10:11], v[10:11], v[102:103]
	v_pk_mul_f32 v[6:7], v[6:7], v[106:107]
	v_pk_mul_f32 v[2:3], v[2:3], v[110:111]
	v_pk_mul_f32 v[0:1], v[0:1], v[108:109]
.LBB5_828:
	s_mov_b32 m0, s32
	s_add_i32 s48, s48, 2
	s_add_i32 s24, s25, 0x2000
	s_cmpk_lg_i32 s25, 0x4000
	s_cselect_b32 s24, s24, 0
	v_lshl_add_u64 v[194:195], v[194:195], 0, s[28:29]
	v_lshl_add_u64 v[196:197], v[196:197], 0, s[28:29]
	s_cmp_ge_i32 s48, s30
	v_lshl_add_u64 v[198:199], v[198:199], 0, s[28:29]
	s_cbranch_scc1 .LBB5_837
	s_mov_b32 s34, s3
	s_mov_b32 s33, s25
	s_mov_b32 s3, s24
	s_branch .LBB5_822
.LBB5_830:
	v_max_f32_e32 v76, v76, v76
	v_max_f32_e32 v77, 0, v76
	v_sub_f32_e32 v112, v112, v77
	v_sub_f32_e32 v113, v113, v77
	v_sub_f32_e32 v114, v114, v77
	v_sub_f32_e32 v115, v115, v77
	v_sub_f32_e32 v116, v116, v77
	v_sub_f32_e32 v117, v117, v77
	v_sub_f32_e32 v118, v118, v77
	v_sub_f32_e32 v119, v119, v77
	v_sub_f32_e32 v120, v120, v77
	v_sub_f32_e32 v121, v121, v77
	v_sub_f32_e32 v122, v122, v77
	v_sub_f32_e32 v123, v123, v77
	v_sub_f32_e32 v124, v124, v77
	v_sub_f32_e32 v125, v125, v77
	v_sub_f32_e32 v126, v126, v77
	v_sub_f32_e32 v127, v127, v77
	v_sub_f32_e32 v96, v96, v77
	v_sub_f32_e32 v97, v97, v77
	v_sub_f32_e32 v98, v98, v77
	v_sub_f32_e32 v99, v99, v77
	v_sub_f32_e32 v100, v100, v77
	v_sub_f32_e32 v101, v101, v77
	v_sub_f32_e32 v102, v102, v77
	v_sub_f32_e32 v103, v103, v77
	v_sub_f32_e32 v104, v104, v77
	v_sub_f32_e32 v105, v105, v77
	v_sub_f32_e32 v106, v106, v77
	v_sub_f32_e32 v107, v107, v77
	v_sub_f32_e32 v108, v108, v77
	v_sub_f32_e32 v109, v109, v77
	v_sub_f32_e32 v110, v110, v77
	v_sub_f32_e32 v111, v111, v77
	v_sub_f32_e32 v220, v220, v77
	v_sub_f32_e32 v221, v221, v77
	v_sub_f32_e32 v222, v222, v77
	v_sub_f32_e32 v223, v223, v77
	v_sub_f32_e32 v224, v224, v77
	v_sub_f32_e32 v225, v225, v77
	v_sub_f32_e32 v226, v226, v77
	v_sub_f32_e32 v227, v227, v77
	v_sub_f32_e32 v228, v228, v77
	v_sub_f32_e32 v229, v229, v77
	v_sub_f32_e32 v230, v230, v77
	v_sub_f32_e32 v231, v231, v77
	v_sub_f32_e32 v232, v232, v77
	v_sub_f32_e32 v233, v233, v77
	v_sub_f32_e32 v234, v234, v77
	v_sub_f32_e32 v235, v235, v77
	v_exp_f32_e64 v76, -v77
	s_and_saveexec_b64 s[50:51], s[0:1]
	s_cbranch_execz .LBB5_832
	v_mbcnt_lo_u32_b32 v78, -1, 0
	v_mbcnt_hi_u32_b32 v78, -1, v78
	s_nop 0
	v_and_b32_e32 v78, 31, v78
	v_lshl_add_u32 v78, v78, 2, s80
	ds_write_b32 v78, v76
.LBB5_832:
	s_or_b64 exec, exec, s[50:51]
	v_add_f32_e32 v211, v211, v77
	v_mul_f32_e32 v214, v214, v76
	s_branch .LBB5_823
.LBB5_833:
	v_max_f32_e32 v108, v108, v108
	v_max_f32_e32 v109, 0, v108
	v_sub_f32_e32 v80, v80, v109
	v_sub_f32_e32 v81, v81, v109
	v_sub_f32_e32 v82, v82, v109
	v_sub_f32_e32 v83, v83, v109
	v_sub_f32_e32 v84, v84, v109
	v_sub_f32_e32 v85, v85, v109
	v_sub_f32_e32 v86, v86, v109
	v_sub_f32_e32 v87, v87, v109
	v_sub_f32_e32 v88, v88, v109
	v_sub_f32_e32 v89, v89, v109
	v_sub_f32_e32 v90, v90, v109
	v_sub_f32_e32 v91, v91, v109
	v_sub_f32_e32 v92, v92, v109
	v_sub_f32_e32 v93, v93, v109
	v_sub_f32_e32 v94, v94, v109
	v_sub_f32_e32 v95, v95, v109
	v_sub_f32_e32 v64, v64, v109
	v_sub_f32_e32 v65, v65, v109
	v_sub_f32_e32 v66, v66, v109
	v_sub_f32_e32 v67, v67, v109
	v_sub_f32_e32 v68, v68, v109
	v_sub_f32_e32 v69, v69, v109
	v_sub_f32_e32 v70, v70, v109
	v_sub_f32_e32 v71, v71, v109
	v_sub_f32_e32 v72, v72, v109
	v_sub_f32_e32 v73, v73, v109
	v_sub_f32_e32 v74, v74, v109
	v_sub_f32_e32 v75, v75, v109
	v_sub_f32_e32 v76, v76, v109
	v_sub_f32_e32 v77, v77, v109
	v_sub_f32_e32 v78, v78, v109
	v_sub_f32_e32 v79, v79, v109
	v_sub_f32_e32 v220, v220, v109
	v_sub_f32_e32 v221, v221, v109
	v_sub_f32_e32 v222, v222, v109
	v_sub_f32_e32 v223, v223, v109
	v_sub_f32_e32 v224, v224, v109
	v_sub_f32_e32 v225, v225, v109
	v_sub_f32_e32 v226, v226, v109
	v_sub_f32_e32 v227, v227, v109
	v_sub_f32_e32 v228, v228, v109
	v_sub_f32_e32 v229, v229, v109
	v_sub_f32_e32 v230, v230, v109
	v_sub_f32_e32 v231, v231, v109
	v_sub_f32_e32 v232, v232, v109
	v_sub_f32_e32 v233, v233, v109
	v_sub_f32_e32 v234, v234, v109
	v_sub_f32_e32 v235, v235, v109
	v_exp_f32_e64 v108, -v109
	s_and_saveexec_b64 s[50:51], s[0:1]
	s_cbranch_execz .LBB5_835
	v_mbcnt_lo_u32_b32 v110, -1, 0
	v_mbcnt_hi_u32_b32 v110, -1, v110
	s_nop 0
	v_and_b32_e32 v110, 31, v110
	v_lshl_add_u32 v110, v110, 2, s80
	ds_write_b32 v110, v108

	.amdhsa_kernel _Z4mega4Args
		.amdhsa_group_segment_fixed_size 0
		.amdhsa_private_segment_fixed_size 0
		.amdhsa_kernarg_size 480
		.amdhsa_user_sgpr_count 2
		.amdhsa_user_sgpr_dispatch_ptr 0
		.amdhsa_user_sgpr_queue_ptr 0
		.amdhsa_user_sgpr_kernarg_segment_ptr 1
		.amdhsa_user_sgpr_dispatch_id 0
		.amdhsa_user_sgpr_kernarg_preload_length 0
		.amdhsa_user_sgpr_kernarg_preload_offset 0
		.amdhsa_user_sgpr_private_segment_size 0
		.amdhsa_uses_dynamic_stack 0
		.amdhsa_enable_private_segment 0
		.amdhsa_system_sgpr_workgroup_id_x 1
		.amdhsa_system_sgpr_workgroup_id_y 0
		.amdhsa_system_sgpr_workgroup_id_z 0
		.amdhsa_system_sgpr_workgroup_info 0
		.amdhsa_system_vgpr_workitem_id 2
		.amdhsa_next_free_vgpr 256
		.amdhsa_next_free_sgpr 98
		.amdhsa_accum_offset 256
		.amdhsa_reserve_vcc 1
		.amdhsa_float_round_mode_32 0
		.amdhsa_float_round_mode_16_64 0
		.amdhsa_float_denorm_mode_32 3
		.amdhsa_float_denorm_mode_16_64 3
		.amdhsa_dx10_clamp 1
		.amdhsa_ieee_mode 1
		.amdhsa_fp16_overflow 0
		.amdhsa_tg_split 0
		.amdhsa_exception_fp_ieee_invalid_op 0
		.amdhsa_exception_fp_denorm_src 0
		.amdhsa_exception_fp_ieee_div_zero 0
		.amdhsa_exception_fp_ieee_overflow 0
		.amdhsa_exception_fp_ieee_underflow 0
		.amdhsa_exception_fp_ieee_inexact 0
		.amdhsa_exception_int_div_zero 0
	.end_amdhsa_kernel

amdhsa.kernels:
  - .agpr_count:     0
    .args:
      - .address_space:  global
        .offset:         0
        .size:           8
        .value_kind:     global_buffer
      - .address_space:  global
        .offset:         8
        .size:           8
        .value_kind:     global_buffer
      - .offset:         16
        .size:           4
        .value_kind:     by_value
      - .offset:         20
        .size:           4
        .value_kind:     by_value
      - .offset:         24
        .size:           80
        .value_kind:     by_value
    .group_segment_fixed_size: 16640
    .kernarg_segment_align: 8
    .kernarg_segment_size: 104
    .language:       OpenCL C
    .language_version:
      - 2
      - 0
    .max_flat_workgroup_size: 256
    .name:           _Z9dumb_gemmPKtS0_ii7DumbEpi
    .private_segment_fixed_size: 0
    .sgpr_count:     35
    .sgpr_spill_count: 0
    .symbol:         _Z9dumb_gemmPKtS0_ii7DumbEpi.kd
    .uniform_work_group_size: 1
    .uses_dynamic_stack: false
    .vgpr_count:     52
    .vgpr_spill_count: 0
    .wavefront_size: 64
  - .agpr_count:     0
    .args:
      - .address_space:  global
        .offset:         0
        .size:           8
        .value_kind:     global_buffer
      - .address_space:  global
        .offset:         8
        .size:           8
        .value_kind:     global_buffer
    .group_segment_fixed_size: 0
    .kernarg_segment_align: 8
    .kernarg_segment_size: 16
    .language:       OpenCL C
    .language_version:
      - 2
      - 0
    .max_flat_workgroup_size: 256
    .name:           _Z10dumb_rowssPKfPf
    .private_segment_fixed_size: 0
    .sgpr_count:     14
    .sgpr_spill_count: 0
    .symbol:         _Z10dumb_rowssPKfPf.kd
    .uniform_work_group_size: 1
    .uses_dynamic_stack: false
    .vgpr_count:     8
    .vgpr_spill_count: 0
    .wavefront_size: 64
  - .agpr_count:     0
    .args:
      - .address_space:  global
        .offset:         0
        .size:           8
        .value_kind:     global_buffer
      - .address_space:  global
        .offset:         8
        .size:           8
        .value_kind:     global_buffer
      - .address_space:  global
        .offset:         16
        .size:           8
        .value_kind:     global_buffer
    .group_segment_fixed_size: 0
    .kernarg_segment_align: 8
    .kernarg_segment_size: 24
    .language:       OpenCL C
    .language_version:
      - 2
      - 0
    .max_flat_workgroup_size: 256
    .name:           _Z9dumb_ropePtPKfS1_
    .private_segment_fixed_size: 0
    .sgpr_count:     16
    .sgpr_spill_count: 0
    .symbol:         _Z9dumb_ropePtPKfS1_.kd
    .uniform_work_group_size: 1
    .uses_dynamic_stack: false
    .vgpr_count:     8
    .vgpr_spill_count: 0
    .wavefront_size: 64
  - .agpr_count:     0
    .args:
      - .address_space:  global
        .offset:         0
        .size:           8
        .value_kind:     global_buffer
      - .address_space:  global
        .offset:         8
        .size:           8
        .value_kind:     global_buffer
      - .address_space:  global
        .offset:         16
        .size:           8
        .value_kind:     global_buffer
      - .address_space:  global
        .offset:         24
        .size:           8
        .value_kind:     global_buffer
      - .address_space:  global
        .offset:         32
        .size:           8
        .value_kind:     global_buffer
      - .address_space:  global
        .offset:         40
        .size:           8
        .value_kind:     global_buffer
      - .address_space:  global
        .offset:         48
        .size:           8
        .value_kind:     global_buffer
      - .address_space:  global
        .offset:         56
        .size:           8
        .value_kind:     global_buffer
      - .address_space:  global
        .offset:         64
        .size:           8
        .value_kind:     global_buffer
      - .address_space:  global
        .offset:         72
        .size:           8
        .value_kind:     global_buffer
    .group_segment_fixed_size: 0
    .kernarg_segment_align: 8
    .kernarg_segment_size: 80
    .language:       OpenCL C
    .language_version:
      - 2
      - 0
    .max_flat_workgroup_size: 64
    .name:           _Z8dumb_ssmPKtPtPKfS3_S3_S3_S3_S3_S3_S3_
    .private_segment_fixed_size: 0
    .sgpr_count:     60
    .sgpr_spill_count: 0
    .symbol:         _Z8dumb_ssmPKtPtPKfS3_S3_S3_S3_S3_S3_S3_.kd
    .uniform_work_group_size: 1
    .uses_dynamic_stack: false
    .vgpr_count:     120
    .vgpr_spill_count: 0
    .wavefront_size: 64
  - .agpr_count:     0
    .args:
      - .address_space:  global
        .offset:         0
        .size:           8
        .value_kind:     global_buffer
      - .address_space:  global
        .offset:         8
        .size:           8
        .value_kind:     global_buffer
      - .address_space:  global
        .offset:         16
        .size:           8
        .value_kind:     global_buffer
      - .address_space:  global
        .offset:         24
        .size:           8
        .value_kind:     global_buffer
      - .address_space:  global
        .offset:         32
        .size:           8
        .value_kind:     global_buffer
    .group_segment_fixed_size: 33032
    .kernarg_segment_align: 8
    .kernarg_segment_size: 40
    .language:       OpenCL C
    .language_version:
      - 2
      - 0
    .max_flat_workgroup_size: 128
    .name:           _Z9dumb_attnPKtS0_S0_PtS1_
    .private_segment_fixed_size: 0
    .sgpr_count:     28
    .sgpr_spill_count: 0
    .symbol:         _Z9dumb_attnPKtS0_S0_PtS1_.kd
    .uniform_work_group_size: 1
    .uses_dynamic_stack: false
    .vgpr_count:     137
    .vgpr_spill_count: 0
    .wavefront_size: 64
  - .agpr_count:     0
    .args:
      - .offset:         0
        .size:           224
        .value_kind:     by_value
      - .offset:         224
        .size:           4
        .value_kind:     hidden_block_count_x
      - .offset:         228
        .size:           4
        .value_kind:     hidden_block_count_y
      - .offset:         232
        .size:           4
        .value_kind:     hidden_block_count_z
      - .offset:         236
        .size:           2
        .value_kind:     hidden_group_size_x
      - .offset:         238
        .size:           2
        .value_kind:     hidden_group_size_y
      - .offset:         240
        .size:           2
        .value_kind:     hidden_group_size_z
      - .offset:         242
        .size:           2
        .value_kind:     hidden_remainder_x
      - .offset:         244
        .size:           2
        .value_kind:     hidden_remainder_y
      - .offset:         246
        .size:           2
        .value_kind:     hidden_remainder_z
      - .offset:         264
        .size:           8
        .value_kind:     hidden_global_offset_x
      - .offset:         272
        .size:           8
        .value_kind:     hidden_global_offset_y
      - .offset:         280
        .size:           8
        .value_kind:     hidden_global_offset_z
      - .offset:         288
        .size:           2
        .value_kind:     hidden_grid_dims
      - .offset:         312
        .size:           8
        .value_kind:     hidden_multigrid_sync_arg
      - .offset:         344
        .size:           4
        .value_kind:     hidden_dynamic_lds_size
    .group_segment_fixed_size: 0
    .kernarg_segment_align: 8
    .kernarg_segment_size: 480
    .language:       OpenCL C
    .language_version:
      - 2
      - 0
    .max_flat_workgroup_size: 512
    .name:           _Z4mega4Args
    .private_segment_fixed_size: 0
    .sgpr_count:     104
    .sgpr_spill_count: 45
    .symbol:         _Z4mega4Args.kd
    .uniform_work_group_size: 1
    .uses_dynamic_stack: false
    .vgpr_count:     256
    .vgpr_spill_count: 0
    .wavefront_size: 64
